# grid barrier: XCD leader forwards the local release before waiting on its own flag atomic and cache invalidate
# speedup vs baseline: 1.0039x; 1.0039x over previous
; DEV unsigned xb_ld(unsigned* p) { return __hip_atomic_load(p, __ATOMIC_RELAXED, __HIP_MEMORY_SCOPE_AGENT); }
; DEV unsigned xb_add(unsigned* p, unsigned v) { return __hip_atomic_fetch_add(p, v, __ATOMIC_RELAXED, __HIP_MEMORY_SCOPE_AGENT); }
; #define XB_SPIN(cond, bar) do { unsigned _sp = 0; while (cond) { __builtin_amdgcn_s_sleep(1); \
;     if ((++_sp & 255u) == 0u) { if (xb_ld(&(bar)[XB_TMO])) break; if (_sp > XB_SPIN_CAP) { atomicAdd(&(bar)[XB_TMO], 1u); break; } } } } while (0)
; DEV void xcd_barrier(const XcdBarrier& b) {
;     ...
;       __builtin_amdgcn_fence(__ATOMIC_ACQUIRE, "agent");
;       xb_add(&bar[XB_XGEN(b.x)], 1u);
;       asm volatile("s_waitcnt vmcnt(0)" ::: "memory");
;     } else {
;       XB_SPIN(xb_ld(&bar[XB_XGEN(b.x)]) == gen, bar);
;       __builtin_amdgcn_fence(__ATOMIC_ACQUIRE, "agent");
;       asm volatile("s_waitcnt vmcnt(0)" ::: "memory");
;     }
;   }
;   __syncthreads();
.LBB0_129:
	s_or_b64 exec, exec, s[2:3]
	s_mov_b64 s[2:3], exec
	v_mbcnt_lo_u32_b32 v0, s2, 0
	v_mbcnt_hi_u32_b32 v0, s3, v0
	v_cmp_eq_u32_e32 vcc, 0, v0
	s_and_saveexec_b64 s[6:7], vcc
	s_cbranch_execz .LBB0_131
	s_bcnt1_i32_b64 s2, s[2:3]
	v_mov_b32_e32 v0, s2
	v_readlane_b32 s2, v252, 36
	v_readlane_b32 s3, v252, 37
	s_nop 4
	global_atomic_add v1, v0, s[2:3]
.LBB0_131:
	s_or_b64 exec, exec, s[6:7]
	s_waitcnt vmcnt(0)
	buffer_inv sc1
	s_waitcnt vmcnt(0)
.LBB0_132:
	s_or_b64 exec, exec, s[0:1]
	s_waitcnt lgkmcnt(0)
	s_barrier
	s_cbranch_execz .LBB0_10

; DEV unsigned xb_ld(unsigned* p) { return __hip_atomic_load(p, __ATOMIC_RELAXED, __HIP_MEMORY_SCOPE_AGENT); }
; DEV unsigned xb_add(unsigned* p, unsigned v) { return __hip_atomic_fetch_add(p, v, __ATOMIC_RELAXED, __HIP_MEMORY_SCOPE_AGENT); }
; #define XB_SPIN(cond, bar) do { unsigned _sp = 0; while (cond) { __builtin_amdgcn_s_sleep(1); \
;     if ((++_sp & 255u) == 0u) { if (xb_ld(&(bar)[XB_TMO])) break; if (_sp > XB_SPIN_CAP) { atomicAdd(&(bar)[XB_TMO], 1u); break; } } } } while (0)
; DEV void xcd_barrier(const XcdBarrier& b) {
;     ...
;       __builtin_amdgcn_fence(__ATOMIC_ACQUIRE, "agent");
;       xb_add(&bar[XB_XGEN(b.x)], 1u);
;       asm volatile("s_waitcnt vmcnt(0)" ::: "memory");
;     } else {
;       XB_SPIN(xb_ld(&bar[XB_XGEN(b.x)]) == gen, bar);
;       __builtin_amdgcn_fence(__ATOMIC_ACQUIRE, "agent");
;       asm volatile("s_waitcnt vmcnt(0)" ::: "memory");
;     }
;   }
;   __syncthreads();
.LBB0_1192:
	s_or_b64 exec, exec, s[6:7]
	s_waitcnt vmcnt(0)
	buffer_inv sc1
	s_waitcnt vmcnt(0)
.LBB0_1193:
	s_or_b64 exec, exec, s[0:1]
	s_waitcnt lgkmcnt(0)
	s_barrier
